# norm row loops: x row loads carry the nt hint
# baseline (speedup 1.0000x reference)
; DI void norm_phase(const float* xp, const float* xs, const float* gvec, const float* MODL  , int sc_off, bf16_t* H, int tid,
;                    const float* P, int nparts, const float* pgate, float* X) {
;     ...
;     for (int it = gw; it < M; it += NGW) {
;         const int row = it < MS ? MP + it : it - MS;
;         const int bi = batch_of(row);
;         const float* xr = (row < MP ? xp : xs) + (size_t)row * 1024; const float* mr = MODL + (size_t)bi * NMOD;
;         f32x4 v[4]; float ss = 0.f;
; #pragma unroll
;         for (int j = 0; j < 4; ++j) v[j] = *(const f32x4*)(xr + 4 * lane + 256 * j);
;         if (row >= MP && nparts > 0) {
;             f32x4 s[4];
; #pragma unroll
;             for (int j = 0; j < 4; ++j) s[j] = (f32x4){0.f, 0.f, 0.f, 0.f};
;             for (int p = 0; p < nparts; ++p) { const float* pr = P + ((size_t)p * 512 + (row - MP)) * 1024 + 4 * lane;
; #pragma unroll
;                 for (int j = 0; j < 4; ++j) s[j] += *(const f32x4*)(pr + 256 * j); }
; #pragma unroll
;             for (int j = 0; j < 4; ++j) { v[j] += *(const f32x4*)(pgate + (size_t)bi * NMOD + 4 * lane + 256 * j) * s[j]; *(f32x4*)(X + (size_t)row * 1024 + 4 * lane + 256 * j) = v[j]; }
;         }
.LBB0_17:
	v_cmp_gt_i32_e32 vcc, s96, v20
	v_mov_b32_e32 v0, 0xfffffe00
	v_mov_b32_e32 v1, 0x4000
	v_cndmask_b32_e32 v0, v0, v1, vcc
	v_cndmask_b32_e64 v1, -1, 0, vcc
	v_add_u32_e32 v16, v0, v20
	v_lshl_add_u64 v[0:1], v[20:21], 0, v[0:1]
	v_lshlrev_b64 v[0:1], 12, v[0:1]
	v_lshl_add_u64 v[30:31], v[26:27], 0, v[0:1]
	global_load_dwordx4 v[12:15], v[30:31], off nt
	global_load_dwordx4 v[8:11], v[30:31], off offset:1024 nt
	global_load_dwordx4 v[4:7], v[30:31], off offset:2048 nt
	global_load_dwordx4 v[0:3], v[30:31], off offset:3072 nt
	s_movk_i32 s6, 0x3fff
	v_cmp_lt_i32_e32 vcc, s6, v16
	s_and_saveexec_b64 s[6:7], vcc
	s_cbranch_execz .LBB0_16
	v_add_u32_e32 v96, 0xffffc000, v16
	v_lshrrev_b32_e32 v16, 2, v96
	v_add_u32_e32 v18, 8, v16
	v_lshlrev_b64 v[16:17], 12, v[96:97]
	v_lshl_add_u64 v[16:17], v[22:23], 0, v[16:17]
	s_mov_b32 s8, 0x18000
	v_mov_b64_e32 v[132:133], v[16:17]
	v_mad_u64_u32 v[164:165], s[8:9], v18, s8, v[24:25]
	global_load_dwordx4 v[170:173], v[164:165], off
	global_load_dwordx4 v[174:177], v[164:165], off offset:1024
	global_load_dwordx4 v[190:193], v[164:165], off offset:2048
	global_load_dwordx4 v[250:253], v[164:165], off offset:3072
	global_load_dwordx4 v[198:201], v[132:133], off
	global_load_dwordx4 v[202:205], v[132:133], off offset:1024
	global_load_dwordx4 v[206:209], v[132:133], off offset:2048
	global_load_dwordx4 v[210:213], v[132:133], off offset:3072
	v_add_co_u32_e32 v132, vcc, 0x200000, v132
	s_nop 1
	v_addc_co_u32_e32 v133, vcc, 0, v133, vcc
	global_load_dwordx4 v[214:217], v[132:133], off
	global_load_dwordx4 v[218:221], v[132:133], off offset:1024
	global_load_dwordx4 v[222:225], v[132:133], off offset:2048
	global_load_dwordx4 v[226:229], v[132:133], off offset:3072
	v_add_co_u32_e32 v132, vcc, 0x200000, v132
	s_nop 1
	v_addc_co_u32_e32 v133, vcc, 0, v133, vcc
	global_load_dwordx4 v[230:233], v[132:133], off
	global_load_dwordx4 v[234:237], v[132:133], off offset:1024
	global_load_dwordx4 v[238:241], v[132:133], off offset:2048
	global_load_dwordx4 v[242:245], v[132:133], off offset:3072
	v_add_co_u32_e32 v132, vcc, 0x200000, v132
	s_nop 1
	v_addc_co_u32_e32 v133, vcc, 0, v133, vcc
	global_load_dwordx4 v[246:249], v[132:133], off
	global_load_dwordx4 v[148:151], v[132:133], off offset:1024
	global_load_dwordx4 v[152:155], v[132:133], off offset:2048
	global_load_dwordx4 v[156:159], v[132:133], off offset:3072
	v_add_co_u32_e32 v132, vcc, 0x200000, v132
	s_nop 1
	v_addc_co_u32_e32 v133, vcc, 0, v133, vcc
	global_load_dwordx4 v[160:163], v[132:133], off
	global_load_dwordx4 v[182:185], v[132:133], off offset:1024
	global_load_dwordx4 v[186:189], v[132:133], off offset:2048
	s_waitcnt vmcnt(18)
	v_pk_add_f32 v[126:127], v[200:201], 0 op_sel_hi:[1,0]
	v_pk_add_f32 v[124:125], v[198:199], 0 op_sel_hi:[1,0]
	global_load_dwordx4 v[198:201], v[132:133], off offset:3072
	s_waitcnt vmcnt(18)
	v_pk_add_f32 v[130:131], v[204:205], 0 op_sel_hi:[1,0]
	v_pk_add_f32 v[128:129], v[202:203], 0 op_sel_hi:[1,0]
	v_add_co_u32_e32 v132, vcc, 0x200000, v132
	s_nop 1
	v_addc_co_u32_e32 v133, vcc, 0, v133, vcc
	global_load_dwordx4 v[202:205], v[132:133], off
	s_waitcnt vmcnt(18)
	v_pk_add_f32 v[140:141], v[208:209], 0 op_sel_hi:[1,0]
	v_pk_add_f32 v[138:139], v[206:207], 0 op_sel_hi:[1,0]
	global_load_dwordx4 v[206:209], v[132:133], off offset:1024
	s_waitcnt vmcnt(18)
	v_pk_add_f32 v[144:145], v[212:213], 0 op_sel_hi:[1,0]
	v_pk_add_f32 v[142:143], v[210:211], 0 op_sel_hi:[1,0]
	global_load_dwordx4 v[210:213], v[132:133], off offset:2048
	s_waitcnt vmcnt(18)
	v_pk_add_f32 v[126:127], v[126:127], v[216:217]
	v_pk_add_f32 v[124:125], v[124:125], v[214:215]
	global_load_dwordx4 v[214:217], v[132:133], off offset:3072
	s_waitcnt vmcnt(18)
	v_pk_add_f32 v[130:131], v[130:131], v[220:221]
	v_pk_add_f32 v[128:129], v[128:129], v[218:219]
	v_add_co_u32_e32 v132, vcc, 0x200000, v132
	s_nop 1
	v_addc_co_u32_e32 v133, vcc, 0, v133, vcc
	global_load_dwordx4 v[218:221], v[132:133], off
	s_waitcnt vmcnt(18)
	v_pk_add_f32 v[140:141], v[140:141], v[224:225]
	v_pk_add_f32 v[138:139], v[138:139], v[222:223]
	global_load_dwordx4 v[222:225], v[132:133], off offset:1024
	s_waitcnt vmcnt(18)
	v_pk_add_f32 v[144:145], v[144:145], v[228:229]
	v_pk_add_f32 v[142:143], v[142:143], v[226:227]
	global_load_dwordx4 v[226:229], v[132:133], off offset:2048
	s_waitcnt vmcnt(18)
	v_pk_add_f32 v[126:127], v[126:127], v[232:233]
	v_pk_add_f32 v[124:125], v[124:125], v[230:231]
	global_load_dwordx4 v[230:233], v[132:133], off offset:3072
	s_waitcnt vmcnt(18)
	v_pk_add_f32 v[130:131], v[130:131], v[236:237]
	v_pk_add_f32 v[128:129], v[128:129], v[234:235]
	v_add_co_u32_e32 v132, vcc, 0x200000, v132
	s_nop 1
	v_addc_co_u32_e32 v133, vcc, 0, v133, vcc
	global_load_dwordx4 v[234:237], v[132:133], off
	s_waitcnt vmcnt(18)
	v_pk_add_f32 v[140:141], v[140:141], v[240:241]
	v_pk_add_f32 v[138:139], v[138:139], v[238:239]
	global_load_dwordx4 v[238:241], v[132:133], off offset:1024
	s_waitcnt vmcnt(18)
	v_pk_add_f32 v[144:145], v[144:145], v[244:245]
	v_pk_add_f32 v[142:143], v[142:143], v[242:243]
	global_load_dwordx4 v[242:245], v[132:133], off offset:2048
	s_waitcnt vmcnt(18)
	v_pk_add_f32 v[126:127], v[126:127], v[248:249]
	v_pk_add_f32 v[124:125], v[124:125], v[246:247]
	global_load_dwordx4 v[246:249], v[132:133], off offset:3072
	s_waitcnt vmcnt(18)
	v_pk_add_f32 v[130:131], v[130:131], v[150:151]
	v_pk_add_f32 v[128:129], v[128:129], v[148:149]
	v_add_co_u32_e32 v132, vcc, 0x200000, v132
	s_nop 1
	v_addc_co_u32_e32 v133, vcc, 0, v133, vcc
	global_load_dwordx4 v[148:151], v[132:133], off
	s_waitcnt vmcnt(18)
; DI void norm_phase(const float* xp, const float* xs, const float* gvec, const float* MODL  , int sc_off, bf16_t* H, int tid,
;                    const float* P, int nparts, const float* pgate, float* X) {
;     ...
;             for (int p = 0; p < nparts; ++p) { const float* pr = P + ((size_t)p * 512 + (row - MP)) * 1024 + 4 * lane;
; #pragma unroll
;                 for (int j = 0; j < 4; ++j) s[j] += *(const f32x4*)(pr + 256 * j); }
	v_pk_add_f32 v[140:141], v[140:141], v[154:155]
	v_pk_add_f32 v[138:139], v[138:139], v[152:153]
	global_load_dwordx4 v[152:155], v[132:133], off offset:1024
	s_waitcnt vmcnt(18)
	v_pk_add_f32 v[144:145], v[144:145], v[158:159]
	v_pk_add_f32 v[142:143], v[142:143], v[156:157]
	global_load_dwordx4 v[156:159], v[132:133], off offset:2048
	s_waitcnt vmcnt(18)
	v_pk_add_f32 v[126:127], v[126:127], v[162:163]
	v_pk_add_f32 v[124:125], v[124:125], v[160:161]
	global_load_dwordx4 v[160:163], v[132:133], off offset:3072
	s_waitcnt vmcnt(18)
	v_pk_add_f32 v[130:131], v[130:131], v[184:185]
	v_pk_add_f32 v[128:129], v[128:129], v[182:183]
	v_add_co_u32_e32 v132, vcc, 0x200000, v132
	s_nop 1
	v_addc_co_u32_e32 v133, vcc, 0, v133, vcc
	global_load_dwordx4 v[182:185], v[132:133], off
	s_waitcnt vmcnt(18)
	v_pk_add_f32 v[140:141], v[140:141], v[188:189]
	v_pk_add_f32 v[138:139], v[138:139], v[186:187]
	global_load_dwordx4 v[186:189], v[132:133], off offset:1024
	s_waitcnt vmcnt(18)
	v_pk_add_f32 v[144:145], v[144:145], v[200:201]
	v_pk_add_f32 v[142:143], v[142:143], v[198:199]
	global_load_dwordx4 v[198:201], v[132:133], off offset:2048
	s_waitcnt vmcnt(18)
	v_pk_add_f32 v[126:127], v[126:127], v[204:205]
	v_pk_add_f32 v[124:125], v[124:125], v[202:203]
	global_load_dwordx4 v[202:205], v[132:133], off offset:3072
	s_waitcnt vmcnt(18)
	v_pk_add_f32 v[130:131], v[130:131], v[208:209]
	v_pk_add_f32 v[128:129], v[128:129], v[206:207]
	v_add_co_u32_e32 v132, vcc, 0x200000, v132
	s_nop 1
	v_addc_co_u32_e32 v133, vcc, 0, v133, vcc
	global_load_dwordx4 v[206:209], v[132:133], off
	s_waitcnt vmcnt(18)
	v_pk_add_f32 v[140:141], v[140:141], v[212:213]
	v_pk_add_f32 v[138:139], v[138:139], v[210:211]
	global_load_dwordx4 v[210:213], v[132:133], off offset:1024
	s_waitcnt vmcnt(18)
	v_pk_add_f32 v[144:145], v[144:145], v[216:217]
	v_pk_add_f32 v[142:143], v[142:143], v[214:215]
	global_load_dwordx4 v[214:217], v[132:133], off offset:2048
	s_waitcnt vmcnt(18)
	v_pk_add_f32 v[126:127], v[126:127], v[220:221]
	v_pk_add_f32 v[124:125], v[124:125], v[218:219]
	global_load_dwordx4 v[218:221], v[132:133], off offset:3072
	s_waitcnt vmcnt(18)
	v_pk_add_f32 v[130:131], v[130:131], v[224:225]
	v_pk_add_f32 v[128:129], v[128:129], v[222:223]
	v_add_co_u32_e32 v132, vcc, 0x200000, v132
	s_nop 1
	v_addc_co_u32_e32 v133, vcc, 0, v133, vcc
	global_load_dwordx4 v[222:225], v[132:133], off
	s_waitcnt vmcnt(18)
	v_pk_add_f32 v[140:141], v[140:141], v[228:229]
	v_pk_add_f32 v[138:139], v[138:139], v[226:227]
	global_load_dwordx4 v[226:229], v[132:133], off offset:1024
	s_waitcnt vmcnt(18)
	v_pk_add_f32 v[144:145], v[144:145], v[232:233]
	v_pk_add_f32 v[142:143], v[142:143], v[230:231]
	global_load_dwordx4 v[230:233], v[132:133], off offset:2048
	s_waitcnt vmcnt(18)
	v_pk_add_f32 v[126:127], v[126:127], v[236:237]
	v_pk_add_f32 v[124:125], v[124:125], v[234:235]
	global_load_dwordx4 v[234:237], v[132:133], off offset:3072
	s_waitcnt vmcnt(18)
	v_pk_add_f32 v[130:131], v[130:131], v[240:241]
	v_pk_add_f32 v[128:129], v[128:129], v[238:239]
	v_add_co_u32_e32 v132, vcc, 0x200000, v132
	s_nop 1
	v_addc_co_u32_e32 v133, vcc, 0, v133, vcc
	global_load_dwordx4 v[238:241], v[132:133], off
	s_waitcnt vmcnt(18)
	v_pk_add_f32 v[140:141], v[140:141], v[244:245]
	v_pk_add_f32 v[138:139], v[138:139], v[242:243]
	global_load_dwordx4 v[242:245], v[132:133], off offset:1024
	s_waitcnt vmcnt(18)
	v_pk_add_f32 v[144:145], v[144:145], v[248:249]
	v_pk_add_f32 v[142:143], v[142:143], v[246:247]
	global_load_dwordx4 v[246:249], v[132:133], off offset:2048
	s_waitcnt vmcnt(18)
	v_pk_add_f32 v[126:127], v[126:127], v[150:151]
	v_pk_add_f32 v[124:125], v[124:125], v[148:149]
	global_load_dwordx4 v[148:151], v[132:133], off offset:3072
	s_waitcnt vmcnt(18)
	v_pk_add_f32 v[130:131], v[130:131], v[154:155]
	v_pk_add_f32 v[128:129], v[128:129], v[152:153]
	v_add_co_u32_e32 v132, vcc, 0x200000, v132
	s_nop 1
	v_addc_co_u32_e32 v133, vcc, 0, v133, vcc
	global_load_dwordx4 v[152:155], v[132:133], off
	s_waitcnt vmcnt(18)
	v_pk_add_f32 v[140:141], v[140:141], v[158:159]
	v_pk_add_f32 v[138:139], v[138:139], v[156:157]
	global_load_dwordx4 v[156:159], v[132:133], off offset:1024
	s_waitcnt vmcnt(18)
	v_pk_add_f32 v[144:145], v[144:145], v[162:163]
	v_pk_add_f32 v[142:143], v[142:143], v[160:161]
	global_load_dwordx4 v[160:163], v[132:133], off offset:2048
	s_waitcnt vmcnt(18)
	v_pk_add_f32 v[126:127], v[126:127], v[184:185]
	v_pk_add_f32 v[124:125], v[124:125], v[182:183]
	global_load_dwordx4 v[182:185], v[132:133], off offset:3072
	s_waitcnt vmcnt(18)
	v_pk_add_f32 v[130:131], v[130:131], v[188:189]
	v_pk_add_f32 v[128:129], v[128:129], v[186:187]
	v_add_co_u32_e32 v132, vcc, 0x200000, v132
	s_nop 1
	v_addc_co_u32_e32 v133, vcc, 0, v133, vcc
	global_load_dwordx4 v[186:189], v[132:133], off
	s_waitcnt vmcnt(18)
	v_pk_add_f32 v[140:141], v[140:141], v[200:201]
	v_pk_add_f32 v[138:139], v[138:139], v[198:199]
	global_load_dwordx4 v[198:201], v[132:133], off offset:1024
	s_waitcnt vmcnt(18)
	v_pk_add_f32 v[144:145], v[144:145], v[204:205]
	v_pk_add_f32 v[142:143], v[142:143], v[202:203]
	global_load_dwordx4 v[202:205], v[132:133], off offset:2048
	s_waitcnt vmcnt(18)
	v_pk_add_f32 v[126:127], v[126:127], v[208:209]
	v_pk_add_f32 v[124:125], v[124:125], v[206:207]
	global_load_dwordx4 v[206:209], v[132:133], off offset:3072
	s_waitcnt vmcnt(18)
	v_pk_add_f32 v[130:131], v[130:131], v[212:213]
	v_pk_add_f32 v[128:129], v[128:129], v[210:211]
	v_add_co_u32_e32 v132, vcc, 0x200000, v132
	s_nop 1
	v_addc_co_u32_e32 v133, vcc, 0, v133, vcc
	global_load_dwordx4 v[210:213], v[132:133], off
	s_waitcnt vmcnt(18)
; DI void norm_phase(const float* xp, const float* xs, const float* gvec, const float* MODL  , int sc_off, bf16_t* H, int tid,
;                    const float* P, int nparts, const float* pgate, float* X) {
;     ...
;             for (int p = 0; p < nparts; ++p) { const float* pr = P + ((size_t)p * 512 + (row - MP)) * 1024 + 4 * lane;
; #pragma unroll
;                 for (int j = 0; j < 4; ++j) s[j] += *(const f32x4*)(pr + 256 * j); }
	v_pk_add_f32 v[140:141], v[140:141], v[216:217]
	v_pk_add_f32 v[138:139], v[138:139], v[214:215]
	global_load_dwordx4 v[214:217], v[132:133], off offset:1024
	s_waitcnt vmcnt(18)
	v_pk_add_f32 v[144:145], v[144:145], v[220:221]
	v_pk_add_f32 v[142:143], v[142:143], v[218:219]
	global_load_dwordx4 v[218:221], v[132:133], off offset:2048
	s_waitcnt vmcnt(18)
	v_pk_add_f32 v[126:127], v[126:127], v[224:225]
	v_pk_add_f32 v[124:125], v[124:125], v[222:223]
	global_load_dwordx4 v[222:225], v[132:133], off offset:3072
	s_waitcnt vmcnt(18)
	v_pk_add_f32 v[130:131], v[130:131], v[228:229]
	v_pk_add_f32 v[128:129], v[128:129], v[226:227]
	v_add_co_u32_e32 v132, vcc, 0x200000, v132
	s_nop 1
	v_addc_co_u32_e32 v133, vcc, 0, v133, vcc
	global_load_dwordx4 v[226:229], v[132:133], off
	s_waitcnt vmcnt(18)
	v_pk_add_f32 v[140:141], v[140:141], v[232:233]
	v_pk_add_f32 v[138:139], v[138:139], v[230:231]
	global_load_dwordx4 v[230:233], v[132:133], off offset:1024
	s_waitcnt vmcnt(18)
	v_pk_add_f32 v[144:145], v[144:145], v[236:237]
	v_pk_add_f32 v[142:143], v[142:143], v[234:235]
	global_load_dwordx4 v[234:237], v[132:133], off offset:2048
	s_waitcnt vmcnt(18)
	v_pk_add_f32 v[126:127], v[126:127], v[240:241]
	v_pk_add_f32 v[124:125], v[124:125], v[238:239]
	global_load_dwordx4 v[238:241], v[132:133], off offset:3072
	s_waitcnt vmcnt(18)
	v_pk_add_f32 v[130:131], v[130:131], v[244:245]
	v_pk_add_f32 v[128:129], v[128:129], v[242:243]
	v_add_co_u32_e32 v132, vcc, 0x200000, v132
	s_nop 1
	v_addc_co_u32_e32 v133, vcc, 0, v133, vcc
	global_load_dwordx4 v[242:245], v[132:133], off
	s_waitcnt vmcnt(18)
	v_pk_add_f32 v[140:141], v[140:141], v[248:249]
	v_pk_add_f32 v[138:139], v[138:139], v[246:247]
	global_load_dwordx4 v[246:249], v[132:133], off offset:1024
	s_waitcnt vmcnt(18)
	v_pk_add_f32 v[144:145], v[144:145], v[150:151]
	v_pk_add_f32 v[142:143], v[142:143], v[148:149]
	global_load_dwordx4 v[148:151], v[132:133], off offset:2048
	s_waitcnt vmcnt(18)
	v_pk_add_f32 v[126:127], v[126:127], v[154:155]
	v_pk_add_f32 v[124:125], v[124:125], v[152:153]
	global_load_dwordx4 v[152:155], v[132:133], off offset:3072
	s_waitcnt vmcnt(18)
	v_pk_add_f32 v[130:131], v[130:131], v[158:159]
	v_pk_add_f32 v[128:129], v[128:129], v[156:157]
	v_add_co_u32_e32 v132, vcc, 0x200000, v132
	s_nop 1
	v_addc_co_u32_e32 v133, vcc, 0, v133, vcc
	global_load_dwordx4 v[156:159], v[132:133], off
	s_waitcnt vmcnt(18)
	v_pk_add_f32 v[140:141], v[140:141], v[162:163]
	v_pk_add_f32 v[138:139], v[138:139], v[160:161]
	global_load_dwordx4 v[160:163], v[132:133], off offset:1024
	s_waitcnt vmcnt(18)
	v_pk_add_f32 v[144:145], v[144:145], v[184:185]
	v_pk_add_f32 v[142:143], v[142:143], v[182:183]
	global_load_dwordx4 v[182:185], v[132:133], off offset:2048
	s_waitcnt vmcnt(18)
	v_pk_add_f32 v[126:127], v[126:127], v[188:189]
	v_pk_add_f32 v[124:125], v[124:125], v[186:187]
	global_load_dwordx4 v[186:189], v[132:133], off offset:3072
	s_waitcnt vmcnt(18)
	v_pk_add_f32 v[130:131], v[130:131], v[200:201]
	v_pk_add_f32 v[128:129], v[128:129], v[198:199]
	v_add_co_u32_e32 v132, vcc, 0x200000, v132
	s_nop 1
	v_addc_co_u32_e32 v133, vcc, 0, v133, vcc
	global_load_dwordx4 v[198:201], v[132:133], off
	s_waitcnt vmcnt(18)
	v_pk_add_f32 v[140:141], v[140:141], v[204:205]
	v_pk_add_f32 v[138:139], v[138:139], v[202:203]
	global_load_dwordx4 v[202:205], v[132:133], off offset:1024
	s_waitcnt vmcnt(18)
	v_pk_add_f32 v[144:145], v[144:145], v[208:209]
	v_pk_add_f32 v[142:143], v[142:143], v[206:207]
	global_load_dwordx4 v[206:209], v[132:133], off offset:2048
	s_waitcnt vmcnt(18)
	v_pk_add_f32 v[126:127], v[126:127], v[212:213]
	v_pk_add_f32 v[124:125], v[124:125], v[210:211]
	global_load_dwordx4 v[210:213], v[132:133], off offset:3072
	s_waitcnt vmcnt(18)
	v_pk_add_f32 v[130:131], v[130:131], v[216:217]
	v_pk_add_f32 v[128:129], v[128:129], v[214:215]
	v_add_co_u32_e32 v132, vcc, 0x200000, v132
	s_nop 1
	v_addc_co_u32_e32 v133, vcc, 0, v133, vcc
	global_load_dwordx4 v[214:217], v[132:133], off
	s_waitcnt vmcnt(18)
	v_pk_add_f32 v[140:141], v[140:141], v[220:221]
	v_pk_add_f32 v[138:139], v[138:139], v[218:219]
	global_load_dwordx4 v[218:221], v[132:133], off offset:1024
	s_waitcnt vmcnt(18)
; DI void norm_phase(const float* xp, const float* xs, const float* gvec, const float* MODL  , int sc_off, bf16_t* H, int tid,
;                    const float* P, int nparts, const float* pgate, float* X) {
;     ...
;             for (int p = 0; p < nparts; ++p) { const float* pr = P + ((size_t)p * 512 + (row - MP)) * 1024 + 4 * lane;
; #pragma unroll
;                 for (int j = 0; j < 4; ++j) s[j] += *(const f32x4*)(pr + 256 * j); }
; #pragma unroll
;             for (int j = 0; j < 4; ++j) { v[j] += *(const f32x4*)(pgate + (size_t)bi * NMOD + 4 * lane + 256 * j) * s[j]; *(f32x4*)(X + (size_t)row * 1024 + 4 * lane + 256 * j) = v[j]; }
;         }
	v_pk_add_f32 v[144:145], v[144:145], v[224:225]
	v_pk_add_f32 v[142:143], v[142:143], v[222:223]
	global_load_dwordx4 v[222:225], v[132:133], off offset:2048
	s_waitcnt vmcnt(18)
	v_pk_add_f32 v[126:127], v[126:127], v[228:229]
	v_pk_add_f32 v[124:125], v[124:125], v[226:227]
	global_load_dwordx4 v[226:229], v[132:133], off offset:3072
	s_waitcnt vmcnt(18)
	v_pk_add_f32 v[130:131], v[130:131], v[232:233]
	v_pk_add_f32 v[128:129], v[128:129], v[230:231]
	v_add_co_u32_e32 v132, vcc, 0x200000, v132
	s_nop 1
	v_addc_co_u32_e32 v133, vcc, 0, v133, vcc
	global_load_dwordx4 v[230:233], v[132:133], off
	s_waitcnt vmcnt(18)
	v_pk_add_f32 v[140:141], v[140:141], v[236:237]
	v_pk_add_f32 v[138:139], v[138:139], v[234:235]
	global_load_dwordx4 v[234:237], v[132:133], off offset:1024
	s_waitcnt vmcnt(18)
	v_pk_add_f32 v[144:145], v[144:145], v[240:241]
	v_pk_add_f32 v[142:143], v[142:143], v[238:239]
	global_load_dwordx4 v[238:241], v[132:133], off offset:2048
	s_waitcnt vmcnt(18)
	v_pk_add_f32 v[126:127], v[126:127], v[244:245]
	v_pk_add_f32 v[124:125], v[124:125], v[242:243]
	global_load_dwordx4 v[242:245], v[132:133], off offset:3072
	s_waitcnt vmcnt(18)
	v_pk_add_f32 v[130:131], v[130:131], v[248:249]
	v_pk_add_f32 v[128:129], v[128:129], v[246:247]
	s_waitcnt vmcnt(17)
	v_pk_add_f32 v[140:141], v[140:141], v[150:151]
	v_pk_add_f32 v[138:139], v[138:139], v[148:149]
	s_waitcnt vmcnt(16)
	v_pk_add_f32 v[144:145], v[144:145], v[154:155]
	v_pk_add_f32 v[142:143], v[142:143], v[152:153]
	s_waitcnt vmcnt(15)
	v_pk_add_f32 v[126:127], v[126:127], v[158:159]
	v_pk_add_f32 v[124:125], v[124:125], v[156:157]
	s_waitcnt vmcnt(14)
	v_pk_add_f32 v[130:131], v[130:131], v[162:163]
	v_pk_add_f32 v[128:129], v[128:129], v[160:161]
	s_waitcnt vmcnt(13)
	v_pk_add_f32 v[140:141], v[140:141], v[184:185]
	v_pk_add_f32 v[138:139], v[138:139], v[182:183]
	s_waitcnt vmcnt(12)
	v_pk_add_f32 v[144:145], v[144:145], v[188:189]
	v_pk_add_f32 v[142:143], v[142:143], v[186:187]
	s_waitcnt vmcnt(11)
	v_pk_add_f32 v[126:127], v[126:127], v[200:201]
	v_pk_add_f32 v[124:125], v[124:125], v[198:199]
	s_waitcnt vmcnt(10)
	v_pk_add_f32 v[130:131], v[130:131], v[204:205]
	v_pk_add_f32 v[128:129], v[128:129], v[202:203]
	s_waitcnt vmcnt(9)
	v_pk_add_f32 v[140:141], v[140:141], v[208:209]
	v_pk_add_f32 v[138:139], v[138:139], v[206:207]
	s_waitcnt vmcnt(8)
	v_pk_add_f32 v[144:145], v[144:145], v[212:213]
	v_pk_add_f32 v[142:143], v[142:143], v[210:211]
	s_waitcnt vmcnt(7)
	v_pk_add_f32 v[126:127], v[126:127], v[216:217]
	v_pk_add_f32 v[124:125], v[124:125], v[214:215]
	s_waitcnt vmcnt(6)
	v_pk_add_f32 v[130:131], v[130:131], v[220:221]
	v_pk_add_f32 v[128:129], v[128:129], v[218:219]
	s_waitcnt vmcnt(5)
	v_pk_add_f32 v[140:141], v[140:141], v[224:225]
	v_pk_add_f32 v[138:139], v[138:139], v[222:223]
	s_waitcnt vmcnt(4)
	v_pk_add_f32 v[144:145], v[144:145], v[228:229]
	v_pk_add_f32 v[142:143], v[142:143], v[226:227]
	s_waitcnt vmcnt(3)
	v_pk_add_f32 v[126:127], v[126:127], v[232:233]
	v_pk_add_f32 v[124:125], v[124:125], v[230:231]
	s_waitcnt vmcnt(2)
	v_pk_add_f32 v[130:131], v[130:131], v[236:237]
	v_pk_add_f32 v[128:129], v[128:129], v[234:235]
	s_waitcnt vmcnt(1)
	v_pk_add_f32 v[140:141], v[140:141], v[240:241]
	v_pk_add_f32 v[138:139], v[138:139], v[238:239]
	s_waitcnt vmcnt(0)
	v_pk_add_f32 v[144:145], v[144:145], v[244:245]
	v_pk_add_f32 v[142:143], v[142:143], v[242:243]
	v_pk_fma_f32 v[14:15], v[126:127], v[172:173], v[14:15]
	v_pk_fma_f32 v[12:13], v[124:125], v[170:171], v[12:13]
	global_store_dwordx4 v[30:31], v[12:15], off
	v_pk_fma_f32 v[10:11], v[130:131], v[176:177], v[10:11]
	v_pk_fma_f32 v[8:9], v[128:129], v[174:175], v[8:9]
	global_store_dwordx4 v[30:31], v[8:11], off offset:1024
	v_pk_fma_f32 v[6:7], v[140:141], v[192:193], v[6:7]
	v_pk_fma_f32 v[4:5], v[138:139], v[190:191], v[4:5]
	global_store_dwordx4 v[30:31], v[4:7], off offset:2048
	v_pk_fma_f32 v[2:3], v[144:145], v[252:253], v[2:3]
	v_pk_fma_f32 v[0:1], v[142:143], v[250:251], v[0:1]
	global_store_dwordx4 v[30:31], v[0:3], off offset:3072
	s_branch .LBB0_16

; DI void norm_phase(const float* xp, const float* xs, const float* gvec, const float* MODL  , int sc_off, bf16_t* H, int tid,
;                    const float* P, int nparts, const float* pgate, float* X) {
;     ...
;     for (int it = gw; it < M; it += NGW) {
;         const int row = it < MS ? MP + it : it - MS;
;         const int bi = batch_of(row);
;         const float* xr = (row < MP ? xp : xs) + (size_t)row * 1024; const float* mr = MODL + (size_t)bi * NMOD;
;         f32x4 v[4]; float ss = 0.f;
; #pragma unroll
;         for (int j = 0; j < 4; ++j) v[j] = *(const f32x4*)(xr + 4 * lane + 256 * j);
;         if (row >= MP && nparts > 0) {
;             f32x4 s[4];
; #pragma unroll
;             for (int j = 0; j < 4; ++j) s[j] = (f32x4){0.f, 0.f, 0.f, 0.f};
;             for (int p = 0; p < nparts; ++p) { const float* pr = P + ((size_t)p * 512 + (row - MP)) * 1024 + 4 * lane;
; #pragma unroll
;                 for (int j = 0; j < 4; ++j) s[j] += *(const f32x4*)(pr + 256 * j); }
.LBB0_228:
	v_cmp_gt_i32_e32 vcc, s96, v16
	v_mov_b32_e32 v0, 0xfffffe00
	v_mov_b32_e32 v1, 0x4000
	v_cndmask_b32_e32 v0, v0, v1, vcc
	v_add_u32_e32 v29, v0, v16
	v_add_u32_e32 v38, 0xffffc000, v29
	v_lshrrev_b32_e32 v2, 2, v38
	s_movk_i32 s6, 0x4000
	v_readlane_b32 s10, v254, 25
	v_ashrrev_i32_e32 v1, 11, v29
	v_add_u32_e32 v2, 8, v2
	v_cmp_gt_i32_e64 s[6:7], s6, v29
	v_readlane_b32 s11, v254, 26
	s_nop 0
	v_cndmask_b32_e64 v31, v2, v1, s[6:7]
	v_mov_b32_e32 v1, s11
	v_mov_b32_e32 v2, s25
	v_cndmask_b32_e64 v3, v1, v2, s[6:7]
	v_mov_b32_e32 v1, s10
	v_mov_b32_e32 v2, s24
	v_cndmask_b32_e64 v2, v1, v2, s[6:7]
	v_cndmask_b32_e64 v1, -1, 0, vcc
	v_lshl_add_u64 v[34:35], v[16:17], 0, v[0:1]
	v_lshlrev_b64 v[0:1], 12, v[34:35]
	v_lshl_add_u64 v[0:1], v[2:3], 0, v[0:1]
	v_lshl_add_u64 v[0:1], v[0:1], 0, v[96:97]
	global_load_dwordx4 v[12:15], v[0:1], off nt
	global_load_dwordx4 v[8:11], v[0:1], off offset:1024 nt
	global_load_dwordx4 v[4:7], v[0:1], off offset:2048 nt
	s_nop 0
	global_load_dwordx4 v[0:3], v[0:1], off offset:3072 nt
	s_movk_i32 s6, 0x6000
	v_mad_i64_i32 v[36:37], s[6:7], v31, s6, 0
	s_movk_i32 s6, 0x3fff
	v_lshlrev_b64 v[34:35], 10, v[34:35]
	v_cmp_lt_i32_e32 vcc, s6, v29
	s_and_saveexec_b64 s[6:7], vcc
	s_cbranch_execz .LBB0_227
	v_mov_b32_e32 v39, v97
	v_lshlrev_b64 v[38:39], 12, v[38:39]
	v_lshl_add_u64 v[38:39], v[18:19], 0, v[38:39]
	v_mov_b64_e32 v[132:133], v[38:39]
	v_lshl_add_u64 v[164:165], v[36:37], 2, v[20:21]
	v_lshl_add_u64 v[178:179], v[34:35], 2, v[22:23]
	global_load_dwordx4 v[170:173], v[164:165], off
	global_load_dwordx4 v[174:177], v[164:165], off offset:1024
	global_load_dwordx4 v[190:193], v[164:165], off offset:2048
	global_load_dwordx4 v[250:253], v[164:165], off offset:3072
	global_load_dwordx4 v[198:201], v[132:133], off
	global_load_dwordx4 v[202:205], v[132:133], off offset:1024
	global_load_dwordx4 v[206:209], v[132:133], off offset:2048
	global_load_dwordx4 v[210:213], v[132:133], off offset:3072
	v_add_co_u32_e32 v132, vcc, 0x200000, v132
	s_nop 1
	v_addc_co_u32_e32 v133, vcc, 0, v133, vcc
	global_load_dwordx4 v[214:217], v[132:133], off
	global_load_dwordx4 v[218:221], v[132:133], off offset:1024
	global_load_dwordx4 v[222:225], v[132:133], off offset:2048
	global_load_dwordx4 v[226:229], v[132:133], off offset:3072
	v_add_co_u32_e32 v132, vcc, 0x200000, v132
	s_nop 1
	v_addc_co_u32_e32 v133, vcc, 0, v133, vcc
	global_load_dwordx4 v[230:233], v[132:133], off
	global_load_dwordx4 v[234:237], v[132:133], off offset:1024
	global_load_dwordx4 v[238:241], v[132:133], off offset:2048
	global_load_dwordx4 v[242:245], v[132:133], off offset:3072
	v_add_co_u32_e32 v132, vcc, 0x200000, v132
	s_nop 1
	v_addc_co_u32_e32 v133, vcc, 0, v133, vcc
	global_load_dwordx4 v[246:249], v[132:133], off
	global_load_dwordx4 v[148:151], v[132:133], off offset:1024
	global_load_dwordx4 v[152:155], v[132:133], off offset:2048
	global_load_dwordx4 v[156:159], v[132:133], off offset:3072
	v_add_co_u32_e32 v132, vcc, 0x200000, v132
	s_nop 1
	v_addc_co_u32_e32 v133, vcc, 0, v133, vcc
	global_load_dwordx4 v[160:163], v[132:133], off
	global_load_dwordx4 v[182:185], v[132:133], off offset:1024
	global_load_dwordx4 v[186:189], v[132:133], off offset:2048
	s_waitcnt vmcnt(18)
	v_pk_add_f32 v[126:127], v[200:201], 0 op_sel_hi:[1,0]
	v_pk_add_f32 v[124:125], v[198:199], 0 op_sel_hi:[1,0]
	global_load_dwordx4 v[198:201], v[132:133], off offset:3072
	s_waitcnt vmcnt(18)
	v_pk_add_f32 v[130:131], v[204:205], 0 op_sel_hi:[1,0]
	v_pk_add_f32 v[128:129], v[202:203], 0 op_sel_hi:[1,0]
	v_add_co_u32_e32 v132, vcc, 0x200000, v132
	s_nop 1
	v_addc_co_u32_e32 v133, vcc, 0, v133, vcc
	global_load_dwordx4 v[202:205], v[132:133], off
	s_waitcnt vmcnt(18)
	v_pk_add_f32 v[140:141], v[208:209], 0 op_sel_hi:[1,0]
	v_pk_add_f32 v[138:139], v[206:207], 0 op_sel_hi:[1,0]
	global_load_dwordx4 v[206:209], v[132:133], off offset:1024
	s_waitcnt vmcnt(18)
	v_pk_add_f32 v[144:145], v[212:213], 0 op_sel_hi:[1,0]
	v_pk_add_f32 v[142:143], v[210:211], 0 op_sel_hi:[1,0]
	global_load_dwordx4 v[210:213], v[132:133], off offset:2048
	s_waitcnt vmcnt(18)
	v_pk_add_f32 v[126:127], v[126:127], v[216:217]
	v_pk_add_f32 v[124:125], v[124:125], v[214:215]
	global_load_dwordx4 v[214:217], v[132:133], off offset:3072
	s_waitcnt vmcnt(18)
; DI void norm_phase(const float* xp, const float* xs, const float* gvec, const float* MODL  , int sc_off, bf16_t* H, int tid,
;                    const float* P, int nparts, const float* pgate, float* X) {
;     ...
;             for (int p = 0; p < nparts; ++p) { const float* pr = P + ((size_t)p * 512 + (row - MP)) * 1024 + 4 * lane;
; #pragma unroll
;                 for (int j = 0; j < 4; ++j) s[j] += *(const f32x4*)(pr + 256 * j); }
; #pragma unroll
;             for (int j = 0; j < 4; ++j) { v[j] += *(const f32x4*)(pgate + (size_t)bi * NMOD + 4 * lane + 256 * j) * s[j]; *(f32x4*)(X + (size_t)row * 1024 + 4 * lane + 256 * j) = v[j]; }
;         }
	v_pk_add_f32 v[130:131], v[130:131], v[220:221]
	v_pk_add_f32 v[128:129], v[128:129], v[218:219]
	v_add_co_u32_e32 v132, vcc, 0x200000, v132
	s_nop 1
	v_addc_co_u32_e32 v133, vcc, 0, v133, vcc
	global_load_dwordx4 v[218:221], v[132:133], off
	s_waitcnt vmcnt(18)
	v_pk_add_f32 v[140:141], v[140:141], v[224:225]
	v_pk_add_f32 v[138:139], v[138:139], v[222:223]
	global_load_dwordx4 v[222:225], v[132:133], off offset:1024
	s_waitcnt vmcnt(18)
	v_pk_add_f32 v[144:145], v[144:145], v[228:229]
	v_pk_add_f32 v[142:143], v[142:143], v[226:227]
	global_load_dwordx4 v[226:229], v[132:133], off offset:2048
	s_waitcnt vmcnt(18)
	v_pk_add_f32 v[126:127], v[126:127], v[232:233]
	v_pk_add_f32 v[124:125], v[124:125], v[230:231]
	global_load_dwordx4 v[230:233], v[132:133], off offset:3072
	s_waitcnt vmcnt(18)
	v_pk_add_f32 v[130:131], v[130:131], v[236:237]
	v_pk_add_f32 v[128:129], v[128:129], v[234:235]
	v_add_co_u32_e32 v132, vcc, 0x200000, v132
	s_nop 1
	v_addc_co_u32_e32 v133, vcc, 0, v133, vcc
	global_load_dwordx4 v[234:237], v[132:133], off
	s_waitcnt vmcnt(18)
	v_pk_add_f32 v[140:141], v[140:141], v[240:241]
	v_pk_add_f32 v[138:139], v[138:139], v[238:239]
	global_load_dwordx4 v[238:241], v[132:133], off offset:1024
	s_waitcnt vmcnt(18)
	v_pk_add_f32 v[144:145], v[144:145], v[244:245]
	v_pk_add_f32 v[142:143], v[142:143], v[242:243]
	global_load_dwordx4 v[242:245], v[132:133], off offset:2048
	s_waitcnt vmcnt(18)
	v_pk_add_f32 v[126:127], v[126:127], v[248:249]
	v_pk_add_f32 v[124:125], v[124:125], v[246:247]
	global_load_dwordx4 v[246:249], v[132:133], off offset:3072
	s_waitcnt vmcnt(18)
	v_pk_add_f32 v[130:131], v[130:131], v[150:151]
	v_pk_add_f32 v[128:129], v[128:129], v[148:149]
	s_waitcnt vmcnt(17)
	v_pk_add_f32 v[140:141], v[140:141], v[154:155]
	v_pk_add_f32 v[138:139], v[138:139], v[152:153]
	s_waitcnt vmcnt(16)
	v_pk_add_f32 v[144:145], v[144:145], v[158:159]
	v_pk_add_f32 v[142:143], v[142:143], v[156:157]
	s_waitcnt vmcnt(15)
	v_pk_add_f32 v[126:127], v[126:127], v[162:163]
	v_pk_add_f32 v[124:125], v[124:125], v[160:161]
	s_waitcnt vmcnt(14)
	v_pk_add_f32 v[130:131], v[130:131], v[184:185]
	v_pk_add_f32 v[128:129], v[128:129], v[182:183]
	s_waitcnt vmcnt(13)
	v_pk_add_f32 v[140:141], v[140:141], v[188:189]
	v_pk_add_f32 v[138:139], v[138:139], v[186:187]
	s_waitcnt vmcnt(12)
	v_pk_add_f32 v[144:145], v[144:145], v[200:201]
	v_pk_add_f32 v[142:143], v[142:143], v[198:199]
	s_waitcnt vmcnt(11)
	v_pk_add_f32 v[126:127], v[126:127], v[204:205]
	v_pk_add_f32 v[124:125], v[124:125], v[202:203]
	s_waitcnt vmcnt(10)
	v_pk_add_f32 v[130:131], v[130:131], v[208:209]
	v_pk_add_f32 v[128:129], v[128:129], v[206:207]
	s_waitcnt vmcnt(9)
	v_pk_add_f32 v[140:141], v[140:141], v[212:213]
	v_pk_add_f32 v[138:139], v[138:139], v[210:211]
	s_waitcnt vmcnt(8)
	v_pk_add_f32 v[144:145], v[144:145], v[216:217]
	v_pk_add_f32 v[142:143], v[142:143], v[214:215]
	s_waitcnt vmcnt(7)
	v_pk_add_f32 v[126:127], v[126:127], v[220:221]
	v_pk_add_f32 v[124:125], v[124:125], v[218:219]
	s_waitcnt vmcnt(6)
	v_pk_add_f32 v[130:131], v[130:131], v[224:225]
	v_pk_add_f32 v[128:129], v[128:129], v[222:223]
	s_waitcnt vmcnt(5)
	v_pk_add_f32 v[140:141], v[140:141], v[228:229]
	v_pk_add_f32 v[138:139], v[138:139], v[226:227]
	s_waitcnt vmcnt(4)
	v_pk_add_f32 v[144:145], v[144:145], v[232:233]
	v_pk_add_f32 v[142:143], v[142:143], v[230:231]
	s_waitcnt vmcnt(3)
	v_pk_add_f32 v[126:127], v[126:127], v[236:237]
	v_pk_add_f32 v[124:125], v[124:125], v[234:235]
	s_waitcnt vmcnt(2)
	v_pk_add_f32 v[130:131], v[130:131], v[240:241]
	v_pk_add_f32 v[128:129], v[128:129], v[238:239]
	s_waitcnt vmcnt(1)
	v_pk_add_f32 v[140:141], v[140:141], v[244:245]
	v_pk_add_f32 v[138:139], v[138:139], v[242:243]
	s_waitcnt vmcnt(0)
	v_pk_add_f32 v[144:145], v[144:145], v[248:249]
	v_pk_add_f32 v[142:143], v[142:143], v[246:247]
	v_pk_fma_f32 v[14:15], v[126:127], v[172:173], v[14:15]
	v_pk_fma_f32 v[12:13], v[124:125], v[170:171], v[12:13]
	global_store_dwordx4 v[178:179], v[12:15], off
	v_pk_fma_f32 v[10:11], v[130:131], v[176:177], v[10:11]
	v_pk_fma_f32 v[8:9], v[128:129], v[174:175], v[8:9]
	global_store_dwordx4 v[178:179], v[8:11], off offset:1024
	v_pk_fma_f32 v[6:7], v[140:141], v[192:193], v[6:7]
	v_pk_fma_f32 v[4:5], v[138:139], v[190:191], v[4:5]
	global_store_dwordx4 v[178:179], v[4:7], off offset:2048
	v_pk_fma_f32 v[2:3], v[144:145], v[252:253], v[2:3]
	v_pk_fma_f32 v[0:1], v[142:143], v[250:251], v[0:1]
	global_store_dwordx4 v[178:179], v[0:3], off offset:3072
	s_branch .LBB0_227

; DI void norm_phase(const float* xp, const float* xs, const float* gvec, const float* MODL  , int sc_off, bf16_t* H, int tid,
;                    const float* P, int nparts, const float* pgate, float* X) {
;     ...
;     for (int it = gw; it < M; it += NGW) {
;         const int row = it < MS ? MP + it : it - MS;
;         const int bi = batch_of(row);
;         const float* xr = (row < MP ? xp : xs) + (size_t)row * 1024; const float* mr = MODL + (size_t)bi * NMOD;
;         f32x4 v[4]; float ss = 0.f;
; #pragma unroll
;         for (int j = 0; j < 4; ++j) v[j] = *(const f32x4*)(xr + 4 * lane + 256 * j);
;         if (row >= MP && nparts > 0) {
;             f32x4 s[4];
; #pragma unroll
;             for (int j = 0; j < 4; ++j) s[j] = (f32x4){0.f, 0.f, 0.f, 0.f};
;             for (int p = 0; p < nparts; ++p) { const float* pr = P + ((size_t)p * 512 + (row - MP)) * 1024 + 4 * lane;
; #pragma unroll
;                 for (int j = 0; j < 4; ++j) s[j] += *(const f32x4*)(pr + 256 * j); }
.LBB0_1953:
	v_cmp_gt_i32_e32 vcc, s96, v20
	v_mov_b32_e32 v0, 0xfffffe00
	v_mov_b32_e32 v1, 0x4000
	v_cndmask_b32_e32 v0, v0, v1, vcc
	v_add_u32_e32 v17, v0, v20
	v_add_u32_e32 v16, 0xffffc000, v17
	v_lshrrev_b32_e32 v2, 2, v16
	s_movk_i32 s6, 0x4000
	v_ashrrev_i32_e32 v1, 11, v17
	v_add_u32_e32 v2, 8, v2
	v_cmp_gt_i32_e64 s[6:7], s6, v17
	s_nop 1
	v_cndmask_b32_e64 v33, v2, v1, s[6:7]
	v_mov_b32_e32 v1, s13
	v_mov_b32_e32 v2, s85
	v_cndmask_b32_e64 v3, v1, v2, s[6:7]
	v_mov_b32_e32 v1, s12
	v_mov_b32_e32 v2, s84
	v_cndmask_b32_e64 v2, v1, v2, s[6:7]
	v_cndmask_b32_e64 v1, -1, 0, vcc
	v_lshl_add_u64 v[18:19], v[20:21], 0, v[0:1]
	v_lshlrev_b64 v[0:1], 12, v[18:19]
	v_lshl_add_u64 v[0:1], v[2:3], 0, v[0:1]
	v_lshl_add_u64 v[0:1], v[0:1], 0, v[96:97]
	global_load_dwordx4 v[12:15], v[0:1], off nt
	global_load_dwordx4 v[8:11], v[0:1], off offset:1024 nt
	global_load_dwordx4 v[4:7], v[0:1], off offset:2048 nt
	s_nop 0
	global_load_dwordx4 v[0:3], v[0:1], off offset:3072 nt
	s_movk_i32 s6, 0x6000
	v_mad_i64_i32 v[40:41], s[6:7], v33, s6, 0
	s_movk_i32 s6, 0x3fff
	s_nop 0
	v_cmp_lt_i32_e32 vcc, s6, v17
	v_lshlrev_b64 v[38:39], 10, v[18:19]
	s_and_b64 s[8:9], s[10:11], vcc
	s_and_saveexec_b64 s[6:7], s[8:9]
	s_cbranch_execz .LBB0_1952
	v_mov_b32_e32 v17, v97
	v_lshlrev_b64 v[16:17], 12, v[16:17]
	v_lshl_add_u64 v[16:17], v[22:23], 0, v[16:17]
	v_mov_b64_e32 v[132:133], v[16:17]
	v_lshl_add_u64 v[164:165], v[40:41], 2, v[24:25]
	v_lshl_add_u64 v[178:179], v[38:39], 2, v[26:27]
	global_load_dwordx4 v[170:173], v[164:165], off
	global_load_dwordx4 v[174:177], v[164:165], off offset:1024
	global_load_dwordx4 v[190:193], v[164:165], off offset:2048
	global_load_dwordx4 v[250:253], v[164:165], off offset:3072
	global_load_dwordx4 v[198:201], v[132:133], off
	global_load_dwordx4 v[202:205], v[132:133], off offset:1024
	global_load_dwordx4 v[206:209], v[132:133], off offset:2048
	global_load_dwordx4 v[210:213], v[132:133], off offset:3072
	v_add_co_u32_e32 v132, vcc, 0x200000, v132
	s_nop 1
	v_addc_co_u32_e32 v133, vcc, 0, v133, vcc
	global_load_dwordx4 v[214:217], v[132:133], off
	global_load_dwordx4 v[218:221], v[132:133], off offset:1024
	global_load_dwordx4 v[222:225], v[132:133], off offset:2048
	global_load_dwordx4 v[226:229], v[132:133], off offset:3072
	v_add_co_u32_e32 v132, vcc, 0x200000, v132
	s_nop 1
	v_addc_co_u32_e32 v133, vcc, 0, v133, vcc
	global_load_dwordx4 v[230:233], v[132:133], off
	global_load_dwordx4 v[234:237], v[132:133], off offset:1024
	global_load_dwordx4 v[238:241], v[132:133], off offset:2048
	global_load_dwordx4 v[242:245], v[132:133], off offset:3072
	v_add_co_u32_e32 v132, vcc, 0x200000, v132
	s_nop 1
	v_addc_co_u32_e32 v133, vcc, 0, v133, vcc
	global_load_dwordx4 v[246:249], v[132:133], off
	global_load_dwordx4 v[148:151], v[132:133], off offset:1024
	global_load_dwordx4 v[152:155], v[132:133], off offset:2048
	global_load_dwordx4 v[156:159], v[132:133], off offset:3072
	v_add_co_u32_e32 v132, vcc, 0x200000, v132
	s_nop 1
	v_addc_co_u32_e32 v133, vcc, 0, v133, vcc
	global_load_dwordx4 v[160:163], v[132:133], off
	global_load_dwordx4 v[182:185], v[132:133], off offset:1024
	global_load_dwordx4 v[186:189], v[132:133], off offset:2048
	s_waitcnt vmcnt(18)
	v_pk_add_f32 v[126:127], v[200:201], 0 op_sel_hi:[1,0]
	v_pk_add_f32 v[124:125], v[198:199], 0 op_sel_hi:[1,0]
	global_load_dwordx4 v[198:201], v[132:133], off offset:3072
	s_waitcnt vmcnt(18)
	v_pk_add_f32 v[130:131], v[204:205], 0 op_sel_hi:[1,0]
	v_pk_add_f32 v[128:129], v[202:203], 0 op_sel_hi:[1,0]
	v_add_co_u32_e32 v132, vcc, 0x200000, v132
	s_nop 1
	v_addc_co_u32_e32 v133, vcc, 0, v133, vcc
	global_load_dwordx4 v[202:205], v[132:133], off
	s_waitcnt vmcnt(18)
	v_pk_add_f32 v[140:141], v[208:209], 0 op_sel_hi:[1,0]
	v_pk_add_f32 v[138:139], v[206:207], 0 op_sel_hi:[1,0]
	global_load_dwordx4 v[206:209], v[132:133], off offset:1024
	s_waitcnt vmcnt(18)
	v_pk_add_f32 v[144:145], v[212:213], 0 op_sel_hi:[1,0]
	v_pk_add_f32 v[142:143], v[210:211], 0 op_sel_hi:[1,0]
	global_load_dwordx4 v[210:213], v[132:133], off offset:2048
	s_waitcnt vmcnt(18)
	v_pk_add_f32 v[126:127], v[126:127], v[216:217]
	v_pk_add_f32 v[124:125], v[124:125], v[214:215]
	global_load_dwordx4 v[214:217], v[132:133], off offset:3072
	s_waitcnt vmcnt(18)
	v_pk_add_f32 v[130:131], v[130:131], v[220:221]
	v_pk_add_f32 v[128:129], v[128:129], v[218:219]
	v_add_co_u32_e32 v132, vcc, 0x200000, v132
	s_nop 1
	v_addc_co_u32_e32 v133, vcc, 0, v133, vcc
	global_load_dwordx4 v[218:221], v[132:133], off
	s_waitcnt vmcnt(18)
	v_pk_add_f32 v[140:141], v[140:141], v[224:225]
	v_pk_add_f32 v[138:139], v[138:139], v[222:223]
	global_load_dwordx4 v[222:225], v[132:133], off offset:1024
	s_waitcnt vmcnt(18)
	v_pk_add_f32 v[144:145], v[144:145], v[228:229]
	v_pk_add_f32 v[142:143], v[142:143], v[226:227]
	global_load_dwordx4 v[226:229], v[132:133], off offset:2048
	s_waitcnt vmcnt(18)
	v_pk_add_f32 v[126:127], v[126:127], v[232:233]
	v_pk_add_f32 v[124:125], v[124:125], v[230:231]
	global_load_dwordx4 v[230:233], v[132:133], off offset:3072
	s_waitcnt vmcnt(18)
	v_pk_add_f32 v[130:131], v[130:131], v[236:237]
	v_pk_add_f32 v[128:129], v[128:129], v[234:235]
	v_add_co_u32_e32 v132, vcc, 0x200000, v132
	s_nop 1
	v_addc_co_u32_e32 v133, vcc, 0, v133, vcc
	global_load_dwordx4 v[234:237], v[132:133], off
	s_waitcnt vmcnt(18)
	v_pk_add_f32 v[140:141], v[140:141], v[240:241]
	v_pk_add_f32 v[138:139], v[138:139], v[238:239]
	global_load_dwordx4 v[238:241], v[132:133], off offset:1024
	s_waitcnt vmcnt(18)
	v_pk_add_f32 v[144:145], v[144:145], v[244:245]
	v_pk_add_f32 v[142:143], v[142:143], v[242:243]
	global_load_dwordx4 v[242:245], v[132:133], off offset:2048
	s_waitcnt vmcnt(18)
; DI void norm_phase(const float* xp, const float* xs, const float* gvec, const float* MODL  , int sc_off, bf16_t* H, int tid,
;                    const float* P, int nparts, const float* pgate, float* X) {
;     ...
;             for (int p = 0; p < nparts; ++p) { const float* pr = P + ((size_t)p * 512 + (row - MP)) * 1024 + 4 * lane;
; #pragma unroll
;                 for (int j = 0; j < 4; ++j) s[j] += *(const f32x4*)(pr + 256 * j); }
	v_pk_add_f32 v[126:127], v[126:127], v[248:249]
	v_pk_add_f32 v[124:125], v[124:125], v[246:247]
	global_load_dwordx4 v[246:249], v[132:133], off offset:3072
	s_waitcnt vmcnt(18)
	v_pk_add_f32 v[130:131], v[130:131], v[150:151]
	v_pk_add_f32 v[128:129], v[128:129], v[148:149]
	v_add_co_u32_e32 v132, vcc, 0x200000, v132
	s_nop 1
	v_addc_co_u32_e32 v133, vcc, 0, v133, vcc
	global_load_dwordx4 v[148:151], v[132:133], off
	s_waitcnt vmcnt(18)
	v_pk_add_f32 v[140:141], v[140:141], v[154:155]
	v_pk_add_f32 v[138:139], v[138:139], v[152:153]
	global_load_dwordx4 v[152:155], v[132:133], off offset:1024
	s_waitcnt vmcnt(18)
	v_pk_add_f32 v[144:145], v[144:145], v[158:159]
	v_pk_add_f32 v[142:143], v[142:143], v[156:157]
	global_load_dwordx4 v[156:159], v[132:133], off offset:2048
	s_waitcnt vmcnt(18)
	v_pk_add_f32 v[126:127], v[126:127], v[162:163]
	v_pk_add_f32 v[124:125], v[124:125], v[160:161]
	global_load_dwordx4 v[160:163], v[132:133], off offset:3072
	s_waitcnt vmcnt(18)
	v_pk_add_f32 v[130:131], v[130:131], v[184:185]
	v_pk_add_f32 v[128:129], v[128:129], v[182:183]
	v_add_co_u32_e32 v132, vcc, 0x200000, v132
	s_nop 1
	v_addc_co_u32_e32 v133, vcc, 0, v133, vcc
	global_load_dwordx4 v[182:185], v[132:133], off
	s_waitcnt vmcnt(18)
	v_pk_add_f32 v[140:141], v[140:141], v[188:189]
	v_pk_add_f32 v[138:139], v[138:139], v[186:187]
	global_load_dwordx4 v[186:189], v[132:133], off offset:1024
	s_waitcnt vmcnt(18)
	v_pk_add_f32 v[144:145], v[144:145], v[200:201]
	v_pk_add_f32 v[142:143], v[142:143], v[198:199]
	global_load_dwordx4 v[198:201], v[132:133], off offset:2048
	s_waitcnt vmcnt(18)
	v_pk_add_f32 v[126:127], v[126:127], v[204:205]
	v_pk_add_f32 v[124:125], v[124:125], v[202:203]
	global_load_dwordx4 v[202:205], v[132:133], off offset:3072
	s_waitcnt vmcnt(18)
	v_pk_add_f32 v[130:131], v[130:131], v[208:209]
	v_pk_add_f32 v[128:129], v[128:129], v[206:207]
	v_add_co_u32_e32 v132, vcc, 0x200000, v132
	s_nop 1
	v_addc_co_u32_e32 v133, vcc, 0, v133, vcc
	global_load_dwordx4 v[206:209], v[132:133], off
	s_waitcnt vmcnt(18)
	v_pk_add_f32 v[140:141], v[140:141], v[212:213]
	v_pk_add_f32 v[138:139], v[138:139], v[210:211]
	global_load_dwordx4 v[210:213], v[132:133], off offset:1024
	s_waitcnt vmcnt(18)
	v_pk_add_f32 v[144:145], v[144:145], v[216:217]
	v_pk_add_f32 v[142:143], v[142:143], v[214:215]
	global_load_dwordx4 v[214:217], v[132:133], off offset:2048
	s_waitcnt vmcnt(18)
	v_pk_add_f32 v[126:127], v[126:127], v[220:221]
	v_pk_add_f32 v[124:125], v[124:125], v[218:219]
	global_load_dwordx4 v[218:221], v[132:133], off offset:3072
	s_waitcnt vmcnt(18)
	v_pk_add_f32 v[130:131], v[130:131], v[224:225]
	v_pk_add_f32 v[128:129], v[128:129], v[222:223]
	v_add_co_u32_e32 v132, vcc, 0x200000, v132
	s_nop 1
	v_addc_co_u32_e32 v133, vcc, 0, v133, vcc
	global_load_dwordx4 v[222:225], v[132:133], off
	s_waitcnt vmcnt(18)
	v_pk_add_f32 v[140:141], v[140:141], v[228:229]
	v_pk_add_f32 v[138:139], v[138:139], v[226:227]
	global_load_dwordx4 v[226:229], v[132:133], off offset:1024
	s_waitcnt vmcnt(18)
	v_pk_add_f32 v[144:145], v[144:145], v[232:233]
	v_pk_add_f32 v[142:143], v[142:143], v[230:231]
	global_load_dwordx4 v[230:233], v[132:133], off offset:2048
	s_waitcnt vmcnt(18)
	v_pk_add_f32 v[126:127], v[126:127], v[236:237]
	v_pk_add_f32 v[124:125], v[124:125], v[234:235]
	global_load_dwordx4 v[234:237], v[132:133], off offset:3072
	s_waitcnt vmcnt(18)
	v_pk_add_f32 v[130:131], v[130:131], v[240:241]
	v_pk_add_f32 v[128:129], v[128:129], v[238:239]
	v_add_co_u32_e32 v132, vcc, 0x200000, v132
	s_nop 1
	v_addc_co_u32_e32 v133, vcc, 0, v133, vcc
	global_load_dwordx4 v[238:241], v[132:133], off
	s_waitcnt vmcnt(18)
	v_pk_add_f32 v[140:141], v[140:141], v[244:245]
	v_pk_add_f32 v[138:139], v[138:139], v[242:243]
	global_load_dwordx4 v[242:245], v[132:133], off offset:1024
	s_waitcnt vmcnt(18)
	v_pk_add_f32 v[144:145], v[144:145], v[248:249]
	v_pk_add_f32 v[142:143], v[142:143], v[246:247]
	global_load_dwordx4 v[246:249], v[132:133], off offset:2048
	s_waitcnt vmcnt(18)
	v_pk_add_f32 v[126:127], v[126:127], v[150:151]
	v_pk_add_f32 v[124:125], v[124:125], v[148:149]
	global_load_dwordx4 v[148:151], v[132:133], off offset:3072
	s_waitcnt vmcnt(18)
	v_pk_add_f32 v[130:131], v[130:131], v[154:155]
	v_pk_add_f32 v[128:129], v[128:129], v[152:153]
	v_add_co_u32_e32 v132, vcc, 0x200000, v132
	s_nop 1
	v_addc_co_u32_e32 v133, vcc, 0, v133, vcc
	global_load_dwordx4 v[152:155], v[132:133], off
	s_waitcnt vmcnt(18)
	v_pk_add_f32 v[140:141], v[140:141], v[158:159]
	v_pk_add_f32 v[138:139], v[138:139], v[156:157]
	global_load_dwordx4 v[156:159], v[132:133], off offset:1024
	s_waitcnt vmcnt(18)
	v_pk_add_f32 v[144:145], v[144:145], v[162:163]
	v_pk_add_f32 v[142:143], v[142:143], v[160:161]
	global_load_dwordx4 v[160:163], v[132:133], off offset:2048
	s_waitcnt vmcnt(18)
	v_pk_add_f32 v[126:127], v[126:127], v[184:185]
	v_pk_add_f32 v[124:125], v[124:125], v[182:183]
	global_load_dwordx4 v[182:185], v[132:133], off offset:3072
	s_waitcnt vmcnt(18)
	v_pk_add_f32 v[130:131], v[130:131], v[188:189]
	v_pk_add_f32 v[128:129], v[128:129], v[186:187]
	v_add_co_u32_e32 v132, vcc, 0x200000, v132
	s_nop 1
	v_addc_co_u32_e32 v133, vcc, 0, v133, vcc
	global_load_dwordx4 v[186:189], v[132:133], off
	s_waitcnt vmcnt(18)
	v_pk_add_f32 v[140:141], v[140:141], v[200:201]
	v_pk_add_f32 v[138:139], v[138:139], v[198:199]
	global_load_dwordx4 v[198:201], v[132:133], off offset:1024
	s_waitcnt vmcnt(18)
	v_pk_add_f32 v[144:145], v[144:145], v[204:205]
	v_pk_add_f32 v[142:143], v[142:143], v[202:203]
	global_load_dwordx4 v[202:205], v[132:133], off offset:2048
	s_waitcnt vmcnt(18)
; DI void norm_phase(const float* xp, const float* xs, const float* gvec, const float* MODL  , int sc_off, bf16_t* H, int tid,
;                    const float* P, int nparts, const float* pgate, float* X) {
;     ...
;             for (int p = 0; p < nparts; ++p) { const float* pr = P + ((size_t)p * 512 + (row - MP)) * 1024 + 4 * lane;
; #pragma unroll
;                 for (int j = 0; j < 4; ++j) s[j] += *(const f32x4*)(pr + 256 * j); }
	v_pk_add_f32 v[126:127], v[126:127], v[208:209]
	v_pk_add_f32 v[124:125], v[124:125], v[206:207]
	global_load_dwordx4 v[206:209], v[132:133], off offset:3072
	s_waitcnt vmcnt(18)
	v_pk_add_f32 v[130:131], v[130:131], v[212:213]
	v_pk_add_f32 v[128:129], v[128:129], v[210:211]
	v_add_co_u32_e32 v132, vcc, 0x200000, v132
	s_nop 1
	v_addc_co_u32_e32 v133, vcc, 0, v133, vcc
	global_load_dwordx4 v[210:213], v[132:133], off
	s_waitcnt vmcnt(18)
	v_pk_add_f32 v[140:141], v[140:141], v[216:217]
	v_pk_add_f32 v[138:139], v[138:139], v[214:215]
	global_load_dwordx4 v[214:217], v[132:133], off offset:1024
	s_waitcnt vmcnt(18)
	v_pk_add_f32 v[144:145], v[144:145], v[220:221]
	v_pk_add_f32 v[142:143], v[142:143], v[218:219]
	global_load_dwordx4 v[218:221], v[132:133], off offset:2048
	s_waitcnt vmcnt(18)
	v_pk_add_f32 v[126:127], v[126:127], v[224:225]
	v_pk_add_f32 v[124:125], v[124:125], v[222:223]
	global_load_dwordx4 v[222:225], v[132:133], off offset:3072
	s_waitcnt vmcnt(18)
	v_pk_add_f32 v[130:131], v[130:131], v[228:229]
	v_pk_add_f32 v[128:129], v[128:129], v[226:227]
	v_add_co_u32_e32 v132, vcc, 0x200000, v132
	s_nop 1
	v_addc_co_u32_e32 v133, vcc, 0, v133, vcc
	global_load_dwordx4 v[226:229], v[132:133], off
	s_waitcnt vmcnt(18)
	v_pk_add_f32 v[140:141], v[140:141], v[232:233]
	v_pk_add_f32 v[138:139], v[138:139], v[230:231]
	global_load_dwordx4 v[230:233], v[132:133], off offset:1024
	s_waitcnt vmcnt(18)
	v_pk_add_f32 v[144:145], v[144:145], v[236:237]
	v_pk_add_f32 v[142:143], v[142:143], v[234:235]
	global_load_dwordx4 v[234:237], v[132:133], off offset:2048
	s_waitcnt vmcnt(18)
	v_pk_add_f32 v[126:127], v[126:127], v[240:241]
	v_pk_add_f32 v[124:125], v[124:125], v[238:239]
	global_load_dwordx4 v[238:241], v[132:133], off offset:3072
	s_waitcnt vmcnt(18)
	v_pk_add_f32 v[130:131], v[130:131], v[244:245]
	v_pk_add_f32 v[128:129], v[128:129], v[242:243]
	v_add_co_u32_e32 v132, vcc, 0x200000, v132
	s_nop 1
	v_addc_co_u32_e32 v133, vcc, 0, v133, vcc
	global_load_dwordx4 v[242:245], v[132:133], off
	s_waitcnt vmcnt(18)
	v_pk_add_f32 v[140:141], v[140:141], v[248:249]
	v_pk_add_f32 v[138:139], v[138:139], v[246:247]
	global_load_dwordx4 v[246:249], v[132:133], off offset:1024
	s_waitcnt vmcnt(18)
	v_pk_add_f32 v[144:145], v[144:145], v[150:151]
	v_pk_add_f32 v[142:143], v[142:143], v[148:149]
	global_load_dwordx4 v[148:151], v[132:133], off offset:2048
	s_waitcnt vmcnt(18)
	v_pk_add_f32 v[126:127], v[126:127], v[154:155]
	v_pk_add_f32 v[124:125], v[124:125], v[152:153]
	global_load_dwordx4 v[152:155], v[132:133], off offset:3072
	s_waitcnt vmcnt(18)
	v_pk_add_f32 v[130:131], v[130:131], v[158:159]
	v_pk_add_f32 v[128:129], v[128:129], v[156:157]
	v_add_co_u32_e32 v132, vcc, 0x200000, v132
	s_nop 1
	v_addc_co_u32_e32 v133, vcc, 0, v133, vcc
	global_load_dwordx4 v[156:159], v[132:133], off
	s_waitcnt vmcnt(18)
	v_pk_add_f32 v[140:141], v[140:141], v[162:163]
	v_pk_add_f32 v[138:139], v[138:139], v[160:161]
	global_load_dwordx4 v[160:163], v[132:133], off offset:1024
	s_waitcnt vmcnt(18)
	v_pk_add_f32 v[144:145], v[144:145], v[184:185]
	v_pk_add_f32 v[142:143], v[142:143], v[182:183]
	global_load_dwordx4 v[182:185], v[132:133], off offset:2048
	s_waitcnt vmcnt(18)
	v_pk_add_f32 v[126:127], v[126:127], v[188:189]
	v_pk_add_f32 v[124:125], v[124:125], v[186:187]
	global_load_dwordx4 v[186:189], v[132:133], off offset:3072
	s_waitcnt vmcnt(18)
	v_pk_add_f32 v[130:131], v[130:131], v[200:201]
	v_pk_add_f32 v[128:129], v[128:129], v[198:199]
	v_add_co_u32_e32 v132, vcc, 0x200000, v132
	s_nop 1
	v_addc_co_u32_e32 v133, vcc, 0, v133, vcc
	global_load_dwordx4 v[198:201], v[132:133], off
	s_waitcnt vmcnt(18)
	v_pk_add_f32 v[140:141], v[140:141], v[204:205]
	v_pk_add_f32 v[138:139], v[138:139], v[202:203]
	global_load_dwordx4 v[202:205], v[132:133], off offset:1024
	s_waitcnt vmcnt(18)
	v_pk_add_f32 v[144:145], v[144:145], v[208:209]
	v_pk_add_f32 v[142:143], v[142:143], v[206:207]
	global_load_dwordx4 v[206:209], v[132:133], off offset:2048
	s_waitcnt vmcnt(18)
	v_pk_add_f32 v[126:127], v[126:127], v[212:213]
	v_pk_add_f32 v[124:125], v[124:125], v[210:211]
	global_load_dwordx4 v[210:213], v[132:133], off offset:3072
	s_waitcnt vmcnt(18)
	v_pk_add_f32 v[130:131], v[130:131], v[216:217]
	v_pk_add_f32 v[128:129], v[128:129], v[214:215]
	v_add_co_u32_e32 v132, vcc, 0x200000, v132
	s_nop 1
	v_addc_co_u32_e32 v133, vcc, 0, v133, vcc
	global_load_dwordx4 v[214:217], v[132:133], off
	s_waitcnt vmcnt(18)
; DI void norm_phase(const float* xp, const float* xs, const float* gvec, const float* MODL  , int sc_off, bf16_t* H, int tid,
;                    const float* P, int nparts, const float* pgate, float* X) {
;     ...
;             for (int p = 0; p < nparts; ++p) { const float* pr = P + ((size_t)p * 512 + (row - MP)) * 1024 + 4 * lane;
; #pragma unroll
;                 for (int j = 0; j < 4; ++j) s[j] += *(const f32x4*)(pr + 256 * j); }
; #pragma unroll
;             for (int j = 0; j < 4; ++j) { v[j] += *(const f32x4*)(pgate + (size_t)bi * NMOD + 4 * lane + 256 * j) * s[j]; *(f32x4*)(X + (size_t)row * 1024 + 4 * lane + 256 * j) = v[j]; }
	v_pk_add_f32 v[140:141], v[140:141], v[220:221]
	v_pk_add_f32 v[138:139], v[138:139], v[218:219]
	global_load_dwordx4 v[218:221], v[132:133], off offset:1024
	s_waitcnt vmcnt(18)
	v_pk_add_f32 v[144:145], v[144:145], v[224:225]
	v_pk_add_f32 v[142:143], v[142:143], v[222:223]
	global_load_dwordx4 v[222:225], v[132:133], off offset:2048
	s_waitcnt vmcnt(18)
	v_pk_add_f32 v[126:127], v[126:127], v[228:229]
	v_pk_add_f32 v[124:125], v[124:125], v[226:227]
	global_load_dwordx4 v[226:229], v[132:133], off offset:3072
	s_waitcnt vmcnt(18)
	v_pk_add_f32 v[130:131], v[130:131], v[232:233]
	v_pk_add_f32 v[128:129], v[128:129], v[230:231]
	v_add_co_u32_e32 v132, vcc, 0x200000, v132
	s_nop 1
	v_addc_co_u32_e32 v133, vcc, 0, v133, vcc
	global_load_dwordx4 v[230:233], v[132:133], off
	s_waitcnt vmcnt(18)
	v_pk_add_f32 v[140:141], v[140:141], v[236:237]
	v_pk_add_f32 v[138:139], v[138:139], v[234:235]
	global_load_dwordx4 v[234:237], v[132:133], off offset:1024
	s_waitcnt vmcnt(18)
	v_pk_add_f32 v[144:145], v[144:145], v[240:241]
	v_pk_add_f32 v[142:143], v[142:143], v[238:239]
	global_load_dwordx4 v[238:241], v[132:133], off offset:2048
	s_waitcnt vmcnt(18)
	v_pk_add_f32 v[126:127], v[126:127], v[244:245]
	v_pk_add_f32 v[124:125], v[124:125], v[242:243]
	global_load_dwordx4 v[242:245], v[132:133], off offset:3072
	s_waitcnt vmcnt(18)
	v_pk_add_f32 v[130:131], v[130:131], v[248:249]
	v_pk_add_f32 v[128:129], v[128:129], v[246:247]
	s_waitcnt vmcnt(17)
	v_pk_add_f32 v[140:141], v[140:141], v[150:151]
	v_pk_add_f32 v[138:139], v[138:139], v[148:149]
	s_waitcnt vmcnt(16)
	v_pk_add_f32 v[144:145], v[144:145], v[154:155]
	v_pk_add_f32 v[142:143], v[142:143], v[152:153]
	s_waitcnt vmcnt(15)
	v_pk_add_f32 v[126:127], v[126:127], v[158:159]
	v_pk_add_f32 v[124:125], v[124:125], v[156:157]
	s_waitcnt vmcnt(14)
	v_pk_add_f32 v[130:131], v[130:131], v[162:163]
	v_pk_add_f32 v[128:129], v[128:129], v[160:161]
	s_waitcnt vmcnt(13)
	v_pk_add_f32 v[140:141], v[140:141], v[184:185]
	v_pk_add_f32 v[138:139], v[138:139], v[182:183]
	s_waitcnt vmcnt(12)
	v_pk_add_f32 v[144:145], v[144:145], v[188:189]
	v_pk_add_f32 v[142:143], v[142:143], v[186:187]
	s_waitcnt vmcnt(11)
	v_pk_add_f32 v[126:127], v[126:127], v[200:201]
	v_pk_add_f32 v[124:125], v[124:125], v[198:199]
	s_waitcnt vmcnt(10)
	v_pk_add_f32 v[130:131], v[130:131], v[204:205]
	v_pk_add_f32 v[128:129], v[128:129], v[202:203]
	s_waitcnt vmcnt(9)
	v_pk_add_f32 v[140:141], v[140:141], v[208:209]
	v_pk_add_f32 v[138:139], v[138:139], v[206:207]
	s_waitcnt vmcnt(8)
	v_pk_add_f32 v[144:145], v[144:145], v[212:213]
	v_pk_add_f32 v[142:143], v[142:143], v[210:211]
	s_waitcnt vmcnt(7)
	v_pk_add_f32 v[126:127], v[126:127], v[216:217]
	v_pk_add_f32 v[124:125], v[124:125], v[214:215]
	s_waitcnt vmcnt(6)
	v_pk_add_f32 v[130:131], v[130:131], v[220:221]
	v_pk_add_f32 v[128:129], v[128:129], v[218:219]
	s_waitcnt vmcnt(5)
	v_pk_add_f32 v[140:141], v[140:141], v[224:225]
	v_pk_add_f32 v[138:139], v[138:139], v[222:223]
	s_waitcnt vmcnt(4)
	v_pk_add_f32 v[144:145], v[144:145], v[228:229]
	v_pk_add_f32 v[142:143], v[142:143], v[226:227]
	s_waitcnt vmcnt(3)
	v_pk_add_f32 v[126:127], v[126:127], v[232:233]
	v_pk_add_f32 v[124:125], v[124:125], v[230:231]
	s_waitcnt vmcnt(2)
	v_pk_add_f32 v[130:131], v[130:131], v[236:237]
	v_pk_add_f32 v[128:129], v[128:129], v[234:235]
	s_waitcnt vmcnt(1)
	v_pk_add_f32 v[140:141], v[140:141], v[240:241]
	v_pk_add_f32 v[138:139], v[138:139], v[238:239]
	s_waitcnt vmcnt(0)
	v_pk_add_f32 v[144:145], v[144:145], v[244:245]
	v_pk_add_f32 v[142:143], v[142:143], v[242:243]
	v_pk_fma_f32 v[14:15], v[126:127], v[172:173], v[14:15]
	v_pk_fma_f32 v[12:13], v[124:125], v[170:171], v[12:13]
	global_store_dwordx4 v[178:179], v[12:15], off
	v_pk_fma_f32 v[10:11], v[130:131], v[176:177], v[10:11]
	v_pk_fma_f32 v[8:9], v[128:129], v[174:175], v[8:9]
	global_store_dwordx4 v[178:179], v[8:11], off offset:1024
	v_pk_fma_f32 v[6:7], v[140:141], v[192:193], v[6:7]
	v_pk_fma_f32 v[4:5], v[138:139], v[190:191], v[4:5]
	global_store_dwordx4 v[178:179], v[4:7], off offset:2048
	v_pk_fma_f32 v[2:3], v[144:145], v[252:253], v[2:3]
	v_pk_fma_f32 v[0:1], v[142:143], v[250:251], v[0:1]
	global_store_dwordx4 v[178:179], v[0:3], off offset:3072
	s_branch .LBB0_1952
